# grid barrier between layer-0 out-proj/LN and layer-1 in-proj replaced by panel barrier + early-posted grid arrival (split barrier); c_r rows taken from own panel
# speedup vs baseline: 1.0058x; 1.0058x over previous
.LBB0_472:
	s_cmp_lg_u32 s34, 0x100
	s_cbranch_scc1 .Lcr_nomap
	v_and_b32_e32 v0, 7, v14
	v_bfe_u32 v1, v14, 9, 1
	v_lshl_or_b32 v0, v1, 3, v0
	v_bfe_u32 v1, v14, 6, 3
	v_lshl_or_b32 v0, v1, 4, v0
	v_bfe_u32 v1, v14, 3, 3
	v_lshl_or_b32 v0, v1, 7, v0
	v_lshl_or_b32 v8, v0, 4, v15

.LBB0_473:
	v_add_co_u32_e32 v26, vcc, 0x1e80000, v12
	s_nop 1
	v_addc_co_u32_e32 v27, vcc, 0, v13, vcc
	global_load_dwordx4 v[32:35], v[10:11], off offset:-256
	global_load_dwordx4 v[36:39], v[26:27], off offset:0
	global_load_dwordx4 v[40:43], v[10:11], off offset:-192
	global_load_dwordx4 v[44:47], v[26:27], off offset:64
	global_load_dwordx4 v[48:51], v[10:11], off offset:-128
	global_load_dwordx4 v[52:55], v[26:27], off offset:128
	global_load_dwordx4 v[56:59], v[10:11], off offset:-64
	global_load_dwordx4 v[60:63], v[26:27], off offset:192
	global_load_dwordx4 v[64:67], v[10:11], off offset:0
	global_load_dwordx4 v[68:71], v[26:27], off offset:256
	global_load_dwordx4 v[72:75], v[10:11], off offset:64
	global_load_dwordx4 v[76:79], v[26:27], off offset:320
	global_load_dwordx4 v[80:83], v[10:11], off offset:128
	global_load_dwordx4 v[84:87], v[26:27], off offset:384
	global_load_dwordx4 v[88:91], v[10:11], off offset:192
	global_load_dwordx4 v[92:95], v[26:27], off offset:448
	global_load_dwordx4 v[96:99], v[10:11], off offset:256
	global_load_dwordx4 v[100:103], v[26:27], off offset:512
	global_load_dwordx4 v[104:107], v[10:11], off offset:320
	global_load_dwordx4 v[108:111], v[26:27], off offset:576
	global_load_dwordx4 v[112:115], v[10:11], off offset:384
	global_load_dwordx4 v[116:119], v[26:27], off offset:640
	global_load_dwordx4 v[120:123], v[10:11], off offset:448
	global_load_dwordx4 v[124:127], v[26:27], off offset:704
	global_load_dwordx4 v[128:131], v[10:11], off offset:512
	global_load_dwordx4 v[132:135], v[26:27], off offset:768
	global_load_dwordx4 v[136:139], v[10:11], off offset:576
	global_load_dwordx4 v[144:147], v[26:27], off offset:832
	global_load_dwordx4 v[148:151], v[10:11], off offset:640
	global_load_dwordx4 v[152:155], v[26:27], off offset:896
	global_load_dwordx4 v[156:159], v[10:11], off offset:704
	global_load_dwordx4 v[160:163], v[26:27], off offset:960
	s_waitcnt vmcnt(30)
	v_mfma_f32_16x16x32_bf16 v[0:3], v[32:35], v[36:39], v[0:3]
	s_waitcnt vmcnt(28)
	v_mfma_f32_16x16x32_bf16 v[0:3], v[40:43], v[44:47], v[0:3]
	s_waitcnt vmcnt(26)
	v_mfma_f32_16x16x32_bf16 v[0:3], v[48:51], v[52:55], v[0:3]
	s_waitcnt vmcnt(24)
	v_mfma_f32_16x16x32_bf16 v[0:3], v[56:59], v[60:63], v[0:3]
	s_waitcnt vmcnt(22)
	v_mfma_f32_16x16x32_bf16 v[0:3], v[64:67], v[68:71], v[0:3]
	s_waitcnt vmcnt(20)
	v_mfma_f32_16x16x32_bf16 v[0:3], v[72:75], v[76:79], v[0:3]
	s_waitcnt vmcnt(18)
	v_mfma_f32_16x16x32_bf16 v[0:3], v[80:83], v[84:87], v[0:3]
	s_waitcnt vmcnt(16)
	v_mfma_f32_16x16x32_bf16 v[0:3], v[88:91], v[92:95], v[0:3]
	global_load_dwordx4 v[32:35], v[10:11], off offset:768
	global_load_dwordx4 v[36:39], v[26:27], off offset:1024
	global_load_dwordx4 v[40:43], v[10:11], off offset:832
	global_load_dwordx4 v[44:47], v[26:27], off offset:1088
	global_load_dwordx4 v[48:51], v[10:11], off offset:896
	global_load_dwordx4 v[52:55], v[26:27], off offset:1152
	global_load_dwordx4 v[56:59], v[10:11], off offset:960
	global_load_dwordx4 v[60:63], v[26:27], off offset:1216
	global_load_dwordx4 v[64:67], v[10:11], off offset:1024
	global_load_dwordx4 v[68:71], v[26:27], off offset:1280
	global_load_dwordx4 v[72:75], v[10:11], off offset:1088
	global_load_dwordx4 v[76:79], v[26:27], off offset:1344
	global_load_dwordx4 v[80:83], v[10:11], off offset:1152
	global_load_dwordx4 v[84:87], v[26:27], off offset:1408
	global_load_dwordx4 v[88:91], v[10:11], off offset:1216
	global_load_dwordx4 v[92:95], v[26:27], off offset:1472
	s_waitcnt vmcnt(30)
	v_mfma_f32_16x16x32_bf16 v[0:3], v[96:99], v[100:103], v[0:3]
	s_waitcnt vmcnt(28)
	v_mfma_f32_16x16x32_bf16 v[0:3], v[104:107], v[108:111], v[0:3]
	s_waitcnt vmcnt(26)
	v_mfma_f32_16x16x32_bf16 v[0:3], v[112:115], v[116:119], v[0:3]
	s_waitcnt vmcnt(24)
	v_mfma_f32_16x16x32_bf16 v[0:3], v[120:123], v[124:127], v[0:3]
	s_waitcnt vmcnt(22)
	v_mfma_f32_16x16x32_bf16 v[0:3], v[128:131], v[132:135], v[0:3]
	s_waitcnt vmcnt(20)
	v_mfma_f32_16x16x32_bf16 v[0:3], v[136:139], v[144:147], v[0:3]
	s_waitcnt vmcnt(18)
	v_mfma_f32_16x16x32_bf16 v[0:3], v[148:151], v[152:155], v[0:3]
	s_waitcnt vmcnt(16)
	v_mfma_f32_16x16x32_bf16 v[0:3], v[156:159], v[160:163], v[0:3]
	global_load_dwordx4 v[96:99], v[10:11], off offset:1280
	global_load_dwordx4 v[100:103], v[26:27], off offset:1536
	global_load_dwordx4 v[104:107], v[10:11], off offset:1344
	global_load_dwordx4 v[108:111], v[26:27], off offset:1600
	global_load_dwordx4 v[112:115], v[10:11], off offset:1408
	global_load_dwordx4 v[116:119], v[26:27], off offset:1664
	global_load_dwordx4 v[120:123], v[10:11], off offset:1472
	global_load_dwordx4 v[124:127], v[26:27], off offset:1728
	global_load_dwordx4 v[128:131], v[10:11], off offset:1536
	global_load_dwordx4 v[132:135], v[26:27], off offset:1792
	global_load_dwordx4 v[136:139], v[10:11], off offset:1600
	global_load_dwordx4 v[144:147], v[26:27], off offset:1856
	global_load_dwordx4 v[148:151], v[10:11], off offset:1664
	global_load_dwordx4 v[152:155], v[26:27], off offset:1920
	global_load_dwordx4 v[156:159], v[10:11], off offset:1728
	global_load_dwordx4 v[160:163], v[26:27], off offset:1984
	s_waitcnt vmcnt(30)
	v_mfma_f32_16x16x32_bf16 v[0:3], v[32:35], v[36:39], v[0:3]
	s_waitcnt vmcnt(28)
	v_mfma_f32_16x16x32_bf16 v[0:3], v[40:43], v[44:47], v[0:3]
	s_waitcnt vmcnt(26)
	v_mfma_f32_16x16x32_bf16 v[0:3], v[48:51], v[52:55], v[0:3]
	s_waitcnt vmcnt(24)
	v_mfma_f32_16x16x32_bf16 v[0:3], v[56:59], v[60:63], v[0:3]
	s_waitcnt vmcnt(22)
	v_mfma_f32_16x16x32_bf16 v[0:3], v[64:67], v[68:71], v[0:3]
	s_waitcnt vmcnt(20)
	v_mfma_f32_16x16x32_bf16 v[0:3], v[72:75], v[76:79], v[0:3]
	s_waitcnt vmcnt(18)
	v_mfma_f32_16x16x32_bf16 v[0:3], v[80:83], v[84:87], v[0:3]
	s_waitcnt vmcnt(16)
	v_mfma_f32_16x16x32_bf16 v[0:3], v[88:91], v[92:95], v[0:3]
	s_waitcnt vmcnt(14)
	v_mfma_f32_16x16x32_bf16 v[0:3], v[96:99], v[100:103], v[0:3]
	s_waitcnt vmcnt(12)
	v_mfma_f32_16x16x32_bf16 v[0:3], v[104:107], v[108:111], v[0:3]
	s_waitcnt vmcnt(10)
	v_mfma_f32_16x16x32_bf16 v[0:3], v[112:115], v[116:119], v[0:3]
	s_waitcnt vmcnt(8)
	v_mfma_f32_16x16x32_bf16 v[0:3], v[120:123], v[124:127], v[0:3]
	s_waitcnt vmcnt(6)
	v_mfma_f32_16x16x32_bf16 v[0:3], v[128:131], v[132:135], v[0:3]
	s_waitcnt vmcnt(4)
	v_mfma_f32_16x16x32_bf16 v[0:3], v[136:139], v[144:147], v[0:3]
	s_waitcnt vmcnt(2)
	v_mfma_f32_16x16x32_bf16 v[0:3], v[148:151], v[152:155], v[0:3]
	s_waitcnt vmcnt(0)
	v_mfma_f32_16x16x32_bf16 v[0:3], v[156:159], v[160:163], v[0:3]
	v_mov_b32_e32 v12, v8
	v_ashrrev_i32_e32 v13, 31, v12
	v_add_u32_e32 v14, s8, v14
	s_movk_i32 s6, 0x3ff
	v_lshlrev_b64 v[12:13], 6, v[12:13]
	v_cmp_lt_i32_e32 vcc, s6, v14
	v_lshl_add_u64 v[12:13], v[4:5], 0, v[12:13]
	s_or_b64 s[4:5], vcc, s[4:5]
	v_add_u32_e32 v8, s9, v8
	global_store_dwordx4 v[12:13], v[0:3], off sc1
	s_andn2_b64 exec, exec, s[4:5]
	s_cbranch_execnz .LBB0_472

.LBB0_571:
	s_cmp_ge_i32 s70, s71
	s_mov_b64 s[2:3], -1
	s_cbranch_scc1 .LBB0_23
	s_cmp_lg_u32 s34, 0x100
	s_cbranch_scc1 .LBB0_580
	s_cmp_eq_u32 s70, 5
	s_cbranch_scc1 .Lpb_local
	s_cmp_eq_u32 s70, 6
	s_cbranch_scc1 .Lpb_entry
	s_cmp_eq_u32 s70, 7
	s_cbranch_scc1 .Lpb_entry
	s_cmp_eq_u32 s70, 12
	s_cbranch_scc1 .Lpb_local
	s_cmp_eq_u32 s70, 13
	s_cbranch_scc1 .Lpb_entry
	s_branch .LBB0_580

.Lpb_entry:
	s_waitcnt vmcnt(0)
	s_barrier
	s_mov_b64 s[4:5], exec
	v_readlane_b32 s2, v254, 9
	v_readlane_b32 s3, v254, 10
	s_nop 1
	s_and_b64 s[2:3], s[4:5], s[2:3]
	s_mov_b64 exec, s[2:3]
	s_cbranch_execz .LBB0_22
	buffer_inv sc1
	v_readlane_b32 s6, v254, 0
	v_readlane_b32 s8, v254, 11
	v_readlane_b32 s9, v254, 12
	s_nop 1
	s_and_b32 s7, s6, 7
	s_lshl_b32 s7, s7, 3
	s_bfe_u32 s6, s6, 0x30003
	s_add_i32 s7, s7, s6
	s_lshl_b32 s7, s7, 2
	s_addk_i32 s7, 0x80
	v_mov_b32_e32 v1, s7
	s_add_u32 s8, s8, 0x280
	s_addc_u32 s9, s9, 0
	s_mov_b32 s6, 1
	s_cmp_gt_i32 s70, 6
	s_cbranch_scc0 .Lpb_target
	s_mov_b32 s6, 2
	s_cmp_gt_i32 s70, 7
	s_cbranch_scc0 .Lpb_target
	s_mov_b32 s6, 3
.Lpb_target:
	s_lshl_b32 s6, s6, 2
	s_mov_b32 s10, 0
	s_nop 4
	global_atomic_add v1, v209, s[8:9]
	s_cmp_eq_u32 s70, 6
	s_cbranch_scc0 .Lpb_spin
	global_atomic_add v177, v209, s[8:9]
.Lpb_spin:
	global_load_dword v0, v1, s[8:9] sc1
	s_waitcnt vmcnt(0)
	v_readfirstlane_b32 s7, v0
	s_nop 1
	s_cmp_ge_u32 s7, s6
	s_cbranch_scc1 .Lpb_done
	s_sleep 1
	s_add_i32 s10, s10, 1
	s_cmp_lt_u32 s10, 0x8000
	s_cbranch_scc1 .Lpb_spin
.Lpb_done:
	s_cmp_eq_u32 s70, 7
	s_cbranch_scc0 .LBB0_22
	s_mov_b32 s10, 0
.Lpb_spin2:
	global_load_dword v0, v177, s[8:9] sc1
	s_waitcnt vmcnt(0)
	v_readfirstlane_b32 s7, v0
	s_nop 1
	s_cmp_ge_u32 s7, s34
	s_cbranch_scc1 .LBB0_22
	s_sleep 1
	s_add_i32 s10, s10, 1
	s_cmp_lt_u32 s10, 0x8000
	s_cbranch_scc1 .Lpb_spin2
	s_branch .LBB0_22
